# code kept warm in L2 inside GEMM phases: 16 KB ahead at each tile-loop header, 8 KB ahead at each K-loop exit
# baseline (speedup 1.0000x reference)
.LBB0_218:
	s_getpc_b64 s[94:95]
	v_mbcnt_lo_u32_b32 v254, -1, 0
	v_mbcnt_hi_u32_b32 v254, -1, v254
	v_lshlrev_b32_e32 v254, 8, v254
	global_load_dword v255, v254, s[94:95]
	global_load_dword v255, v254, s[94:95] offset:128
	s_add_i32 s78, s78, 1
	s_mul_i32 s8, s78, s70
	s_mul_hi_u32 s9, s78, s2
	s_add_i32 s9, s9, s8
	s_mul_i32 s8, s78, s2
	s_add_u32 s40, s8, s3
	s_addc_u32 s41, s9, s71
	v_cmp_gt_i64_e64 s[8:9], s[40:41], v[140:141]
	s_and_b64 vcc, exec, s[8:9]
	s_cbranch_vccnz .LBB0_220
	s_ashr_i32 s11, s40, 31
	s_lshr_b32 s11, s11, 29
	s_add_i32 s11, s40, s11
	s_ashr_i32 s15, s11, 3
	s_and_b32 s11, s11, -8
	s_sub_i32 s11, s40, s11
	s_lshr_b32 s26, s11, 31
	s_or_b32 s26, s26, 0x48
	s_mul_i32 s11, s26, s11
	s_add_i32 s11, s11, s15
	s_mul_hi_i32 s15, s11, 0x2aaaaaab
	s_lshr_b32 s26, s15, 31
	s_ashr_i32 s15, s15, 4
	s_add_i32 s15, s15, s26
	s_lshl_b32 s26, s15, 3
	s_sub_i32 s34, 48, s26
	s_min_i32 s35, s34, 8
	s_abs_i32 s34, s35
	v_cvt_f32_u32_e32 v0, s34
	s_sub_i32 s37, 0, s34
	s_mulk_i32 s15, 0x60
	s_sub_i32 s11, s11, s15
	v_rcp_iflag_f32_e32 v0, v0
	s_abs_i32 s15, s11
	s_xor_b32 s36, s11, s35
	s_ashr_i32 s36, s36, 31
	v_mul_f32_e32 v0, 0x4f7ffffe, v0
	v_cvt_u32_f32_e32 v0, v0
	s_nop 0
	v_readfirstlane_b32 s40, v0
	s_mul_i32 s37, s37, s40
	s_mul_hi_u32 s37, s40, s37
	s_add_i32 s40, s40, s37
	s_mul_hi_u32 s37, s15, s40
	s_mul_i32 s40, s37, s34
	s_sub_i32 s15, s15, s40
	s_add_i32 s41, s37, 1
	s_sub_i32 s40, s15, s34
	s_cmp_ge_u32 s15, s34
	s_cselect_b32 s37, s41, s37
	s_cselect_b32 s15, s40, s15
	s_add_i32 s40, s37, 1
	s_cmp_ge_u32 s15, s34
	s_cselect_b32 s15, s40, s37
	s_xor_b32 s15, s15, s36
	s_sub_i32 s34, s15, s36
	s_mul_i32 s15, s34, s35
	s_sub_i32 s11, s11, s15
	s_add_i32 s36, s11, s26

.LBB0_241:
	s_getpc_b64 s[94:95]
	v_mbcnt_lo_u32_b32 v254, -1, 0
	v_mbcnt_hi_u32_b32 v254, -1, v254
	v_lshlrev_b32_e32 v254, 7, v254
	global_load_dword v255, v254, s[94:95]
	v_lshl_add_u32 v169, s14, 8, v150
	v_lshl_or_b32 v144, s10, 8, v152
	v_mov_b64_e32 v[146:147], s[16:17]
	v_ashrrev_i32_e32 v145, 31, v144
	v_mad_i64_i32 v[146:147], s[10:11], v169, s76, v[146:147]
	v_lshl_add_u64 v[146:147], v[144:145], 1, v[146:147]
	v_cmp_gt_i32_e32 vcc, s77, v144
	s_and_saveexec_b64 s[10:11], vcc
	s_cbranch_execz .LBB0_243
	v_cvt_pk_bf16_f32 v124, v124, v125
	v_cvt_pk_bf16_f32 v125, v126, v127
	v_cvt_pk_bf16_f32 v126, v120, v121
	v_cvt_pk_bf16_f32 v127, v122, v123
	flat_store_dwordx4 v[146:147], v[124:127]

.LBB0_1455:
	s_getpc_b64 s[94:95]
	v_mbcnt_lo_u32_b32 v254, -1, 0
	v_mbcnt_hi_u32_b32 v254, -1, v254
	v_lshlrev_b32_e32 v254, 8, v254
	global_load_dword v255, v254, s[94:95]
	global_load_dword v255, v254, s[94:95] offset:128
	s_add_i32 s82, s82, 1
	s_mul_i32 s8, s82, s76
	s_mul_hi_u32 s9, s82, s2
	s_add_i32 s9, s9, s8
	s_mul_i32 s8, s82, s2
	s_add_u32 s42, s8, s3
	s_addc_u32 s43, s9, s77
	v_cmp_gt_i64_e64 s[8:9], s[42:43], v[140:141]
	s_and_b64 vcc, exec, s[8:9]
	s_cbranch_vccnz .LBB0_1457
	s_ashr_i32 s11, s42, 31
	s_lshr_b32 s11, s11, 29
	s_add_i32 s11, s42, s11
	s_ashr_i32 s21, s11, 3
	s_and_b32 s11, s11, -8
	s_sub_i32 s11, s42, s11
	s_lshr_b32 s26, s11, 31
	s_or_b32 s26, s26, 24
	s_mul_i32 s11, s26, s11
	s_add_i32 s11, s11, s21
	s_ashr_i32 s21, s11, 31
	s_lshr_b32 s21, s21, 27
	s_add_i32 s21, s11, s21
	s_ashr_i32 s26, s21, 5
	s_lshl_b32 s26, s26, 3
	s_sub_i32 s30, 48, s26
	s_min_i32 s31, s30, 8
	s_abs_i32 s30, s31
	v_cvt_f32_u32_e32 v0, s30
	s_sub_i32 s37, 0, s30
	s_andn2_b32 s21, s21, 31
	s_sub_i32 s11, s11, s21
	v_rcp_iflag_f32_e32 v0, v0
	s_abs_i32 s21, s11
	s_xor_b32 s36, s11, s31
	s_ashr_i32 s36, s36, 31
	v_mul_f32_e32 v0, 0x4f7ffffe, v0
	v_cvt_u32_f32_e32 v0, v0
	s_nop 0
	v_readfirstlane_b32 s42, v0
	s_mul_i32 s37, s37, s42
	s_mul_hi_u32 s37, s42, s37
	s_add_i32 s42, s42, s37
	s_mul_hi_u32 s37, s21, s42
	s_mul_i32 s42, s37, s30
	s_sub_i32 s21, s21, s42
	s_add_i32 s43, s37, 1
	s_sub_i32 s42, s21, s30
	s_cmp_ge_u32 s21, s30
	s_cselect_b32 s37, s43, s37
	s_cselect_b32 s21, s42, s21
	s_add_i32 s42, s37, 1
	s_cmp_ge_u32 s21, s30
	s_cselect_b32 s21, s42, s37
	s_xor_b32 s21, s21, s36
	s_sub_i32 s30, s21, s36
	s_mul_i32 s21, s30, s31
	s_sub_i32 s11, s11, s21
	s_add_i32 s36, s11, s26

.LBB0_1478:
	s_getpc_b64 s[94:95]
	v_mbcnt_lo_u32_b32 v254, -1, 0
	v_mbcnt_hi_u32_b32 v254, -1, v254
	v_lshlrev_b32_e32 v254, 7, v254
	global_load_dword v255, v254, s[94:95]
	v_lshl_add_u32 v146, s20, 8, v152
	v_ashrrev_i32_e32 v147, 31, v146
	v_lshl_or_b32 v144, s10, 8, v154
	v_lshlrev_b64 v[148:149], 11, v[146:147]
	v_ashrrev_i32_e32 v145, 31, v144
	v_lshl_add_u64 v[148:149], s[22:23], 0, v[148:149]
	v_lshl_add_u64 v[148:149], v[144:145], 1, v[148:149]
	v_cmp_gt_i32_e32 vcc, s71, v144
	s_and_saveexec_b64 s[10:11], vcc
	s_cbranch_execz .LBB0_1480
	v_cvt_pk_bf16_f32 v124, v124, v125
	v_cvt_pk_bf16_f32 v125, v126, v127
	v_cvt_pk_bf16_f32 v126, v120, v121
	v_cvt_pk_bf16_f32 v127, v122, v123
	flat_store_dwordx4 v[148:149], v[124:127]

.LBB0_1726:
	s_getpc_b64 s[94:95]
	v_mbcnt_lo_u32_b32 v254, -1, 0
	v_mbcnt_hi_u32_b32 v254, -1, v254
	v_lshlrev_b32_e32 v254, 8, v254
	global_load_dword v255, v254, s[94:95]
	global_load_dword v255, v254, s[94:95] offset:128
	s_add_i32 s82, s82, 1
	s_mul_i32 s8, s82, s75
	s_mul_hi_u32 s9, s82, s2
	s_add_i32 s9, s9, s8
	s_mul_i32 s8, s82, s2
	s_add_u32 s10, s8, s3
	s_addc_u32 s11, s9, s76
	v_cmp_gt_i64_e64 s[8:9], s[10:11], v[140:141]
	s_and_b64 vcc, exec, s[8:9]
	s_cbranch_vccnz .LBB0_1728
	s_ashr_i32 s11, s10, 31
	s_lshr_b32 s11, s11, 29
	s_add_i32 s11, s10, s11
	s_ashr_i32 s20, s11, 3
	s_and_b32 s11, s11, -8
	s_sub_i32 s10, s10, s11
	s_lshr_b32 s11, s10, 31
	s_or_b32 s11, s11, 0x60
	s_mul_i32 s10, s11, s10
	s_add_i32 s10, s10, s20
	s_ashr_i32 s11, s10, 31
	s_lshr_b32 s11, s11, 25
	s_add_i32 s11, s10, s11
	s_ashr_i32 s20, s11, 7
	s_lshl_b32 s20, s20, 3
	s_sub_i32 s30, 48, s20
	s_min_i32 s31, s30, 8
	s_abs_i32 s30, s31
	v_cvt_f32_u32_e32 v0, s30
	s_sub_i32 s35, 0, s30
	s_and_b32 s11, s11, 0xffffff80
	s_sub_i32 s10, s10, s11
	v_rcp_iflag_f32_e32 v0, v0
	s_abs_i32 s11, s10
	s_xor_b32 s34, s10, s31
	s_ashr_i32 s34, s34, 31
	v_mul_f32_e32 v0, 0x4f7ffffe, v0
	v_cvt_u32_f32_e32 v0, v0
	s_nop 0
	v_readfirstlane_b32 s36, v0
	s_mul_i32 s35, s35, s36
	s_mul_hi_u32 s35, s36, s35
	s_add_i32 s36, s36, s35
	s_mul_hi_u32 s35, s11, s36
	s_mul_i32 s36, s35, s30
	s_sub_i32 s11, s11, s36
	s_add_i32 s37, s35, 1
	s_sub_i32 s36, s11, s30
	s_cmp_ge_u32 s11, s30
	s_cselect_b32 s35, s37, s35
	s_cselect_b32 s11, s36, s11
	s_add_i32 s36, s35, 1
	s_cmp_ge_u32 s11, s30
	s_cselect_b32 s11, s36, s35
	s_xor_b32 s11, s11, s34
	s_sub_i32 s30, s11, s34
	s_mul_i32 s11, s30, s31
	s_sub_i32 s10, s10, s11
	s_add_i32 s34, s10, s20

.LBB0_1749:
	s_getpc_b64 s[94:95]
	v_mbcnt_lo_u32_b32 v254, -1, 0
	v_mbcnt_hi_u32_b32 v254, -1, v254
	v_lshlrev_b32_e32 v254, 7, v254
	global_load_dword v255, v254, s[94:95]
	v_lshl_add_u32 v146, s44, 8, v151
	v_ashrrev_i32_e32 v147, 31, v146
	v_lshl_or_b32 v144, s42, 8, v153
	v_lshlrev_b64 v[148:149], 13, v[146:147]
	v_ashrrev_i32_e32 v145, 31, v144
	v_lshl_add_u64 v[148:149], s[14:15], 0, v[148:149]
	v_lshl_add_u64 v[148:149], v[144:145], 1, v[148:149]
	v_cmp_gt_i32_e32 vcc, s81, v144
	s_and_saveexec_b64 s[10:11], vcc
	s_cbranch_execz .LBB0_1751
	v_max_f32_e32 v124, 0, v124
	v_max_f32_e32 v125, 0, v125
	v_max_f32_e32 v126, 0, v126
	v_max_f32_e32 v127, 0, v127
	v_max_f32_e32 v120, 0, v120
	v_max_f32_e32 v121, 0, v121
	v_max_f32_e32 v122, 0, v122
	v_max_f32_e32 v123, 0, v123
	v_pk_mul_f32 v[124:125], v[124:125], v[124:125]
	v_pk_mul_f32 v[126:127], v[126:127], v[126:127]
	v_pk_mul_f32 v[120:121], v[120:121], v[120:121]
	v_pk_mul_f32 v[122:123], v[122:123], v[122:123]
	v_cvt_pk_bf16_f32 v120, v120, v121
	v_cvt_pk_bf16_f32 v121, v122, v123
	v_cvt_pk_bf16_f32 v122, v124, v125
	v_cvt_pk_bf16_f32 v123, v126, v127
	flat_store_dwordx4 v[148:149], v[120:123]

.LBB0_1845:
	ds_read_b128 v[180:183], v162
	ds_read_b128 v[184:187], v163
	ds_read_b128 v[188:191], v164
	ds_read_b128 v[192:195], v165
	ds_read_b128 v[196:199], v166
	ds_read_b128 v[200:203], v167
	ds_read_b128 v[204:207], v168
	ds_read_b128 v[208:211], v169
	s_add_u32 s42, s36, s40
	s_addc_u32 s43, s37, s41
	s_add_u32 s42, s42, 0x100
	s_addc_u32 s43, s43, 0
	s_add_u32 s72, s69, s40
	s_addc_u32 s73, s70, s41
	s_cmpk_eq_i32 s40, 0x1f00
	s_cselect_b32 s45, s7, s43
	s_cselect_b32 s44, s21, s42
	s_cselect_b32 s43, s27, s73
	s_cselect_b32 s42, s29, s72
	s_mov_b32 m0, s65
	v_lshl_add_u64 v[244:245], v[156:157], 0, s[40:41]
	ds_read_b128 v[212:215], v160
	ds_read_b128 v[216:219], v160 offset:1024
	ds_read_b128 v[220:223], v160 offset:2048
	ds_read_b128 v[224:227], v160 offset:3072
	ds_read_b128 v[228:231], v160 offset:4096
	ds_read_b128 v[232:235], v160 offset:5120
	ds_read_b128 v[236:239], v160 offset:6144
	ds_read_b128 v[240:243], v160 offset:7168
	global_load_lds_dwordx4 v[244:245], off
	v_lshl_add_u64 v[244:245], v[154:155], 0, s[40:41]
	s_mov_b32 m0, s66
	s_nop 0
	global_load_lds_dwordx4 v[244:245], off
	v_lshl_add_u64 v[244:245], v[152:153], 0, s[40:41]
	s_mov_b32 m0, s67
	s_nop 0
	global_load_lds_dwordx4 v[244:245], off
	v_lshl_add_u64 v[244:245], v[150:151], 0, s[40:41]
	s_mov_b32 m0, s68
	s_nop 0
	global_load_lds_dwordx4 v[244:245], off
	s_waitcnt lgkmcnt(8)
	s_barrier
	s_waitcnt lgkmcnt(0)
	s_setprio 1
	s_waitcnt lgkmcnt(0)
	v_mfma_f32_16x16x32_bf16 v[124:127], v[180:183], v[212:215], v[124:127]
	v_mfma_f32_16x16x32_bf16 v[120:123], v[188:191], v[212:215], v[120:123]
	v_mfma_f32_16x16x32_bf16 v[116:119], v[180:183], v[220:223], v[116:119]
	v_mfma_f32_16x16x32_bf16 v[108:111], v[188:191], v[220:223], v[108:111]
	v_mfma_f32_16x16x32_bf16 v[100:103], v[180:183], v[228:231], v[100:103]
	v_mfma_f32_16x16x32_bf16 v[92:95], v[188:191], v[228:231], v[92:95]
	v_mfma_f32_16x16x32_bf16 v[84:87], v[180:183], v[236:239], v[84:87]
	v_mfma_f32_16x16x32_bf16 v[76:79], v[188:191], v[236:239], v[76:79]
	v_mfma_f32_16x16x32_bf16 v[124:127], v[184:187], v[216:219], v[124:127]
	v_mfma_f32_16x16x32_bf16 v[120:123], v[192:195], v[216:219], v[120:123]
	v_mfma_f32_16x16x32_bf16 v[116:119], v[184:187], v[224:227], v[116:119]
	v_mfma_f32_16x16x32_bf16 v[108:111], v[192:195], v[224:227], v[108:111]
	v_mfma_f32_16x16x32_bf16 v[100:103], v[184:187], v[232:235], v[100:103]
	v_mfma_f32_16x16x32_bf16 v[92:95], v[192:195], v[232:235], v[92:95]
	v_mfma_f32_16x16x32_bf16 v[84:87], v[184:187], v[240:243], v[84:87]
	v_mfma_f32_16x16x32_bf16 v[76:79], v[192:195], v[240:243], v[76:79]
	s_setprio 0
	s_setprio 1
	v_mfma_f32_16x16x32_bf16 v[112:115], v[196:199], v[212:215], v[112:115]
	v_mfma_f32_16x16x32_bf16 v[104:107], v[204:207], v[212:215], v[104:107]
	v_mfma_f32_16x16x32_bf16 v[96:99], v[196:199], v[220:223], v[96:99]
	v_mfma_f32_16x16x32_bf16 v[88:91], v[204:207], v[220:223], v[88:91]
	v_mfma_f32_16x16x32_bf16 v[80:83], v[196:199], v[228:231], v[80:83]
	v_mfma_f32_16x16x32_bf16 v[72:75], v[204:207], v[228:231], v[72:75]
	v_mfma_f32_16x16x32_bf16 v[68:71], v[196:199], v[236:239], v[68:71]
	v_mfma_f32_16x16x32_bf16 v[64:67], v[204:207], v[236:239], v[64:67]
	v_mfma_f32_16x16x32_bf16 v[112:115], v[200:203], v[216:219], v[112:115]
	v_mfma_f32_16x16x32_bf16 v[104:107], v[208:211], v[216:219], v[104:107]
	v_mfma_f32_16x16x32_bf16 v[96:99], v[200:203], v[224:227], v[96:99]
	v_mfma_f32_16x16x32_bf16 v[88:91], v[208:211], v[224:227], v[88:91]
	v_mfma_f32_16x16x32_bf16 v[80:83], v[200:203], v[232:235], v[80:83]
	v_mfma_f32_16x16x32_bf16 v[72:75], v[208:211], v[232:235], v[72:75]
	v_mfma_f32_16x16x32_bf16 v[68:71], v[200:203], v[240:243], v[68:71]
	v_mfma_f32_16x16x32_bf16 v[64:67], v[208:211], v[240:243], v[64:67]
	s_setprio 0
	s_barrier
	s_mov_b32 m0, s50
	v_lshl_add_u64 v[244:245], s[42:43], 0, v[136:137]
	s_add_u32 s72, s42, 0x100000
	ds_read_b128 v[212:215], v160 offset:16384
	ds_read_b128 v[216:219], v160 offset:17408
	ds_read_b128 v[220:223], v160 offset:18432
	ds_read_b128 v[224:227], v160 offset:19456
	ds_read_b128 v[228:231], v160 offset:20480
	ds_read_b128 v[232:235], v160 offset:21504
	ds_read_b128 v[236:239], v160 offset:22528
	ds_read_b128 v[240:243], v160 offset:23552
	global_load_lds_dwordx4 v[244:245], off
	v_lshl_add_u64 v[246:247], s[42:43], 0, v[138:139]
	s_mov_b32 m0, s51
	s_addc_u32 s73, s43, 0
	global_load_lds_dwordx4 v[246:247], off
	v_lshl_add_u64 v[248:249], s[72:73], 0, v[136:137]
	s_mov_b32 m0, s52
	s_nop 0
	global_load_lds_dwordx4 v[248:249], off
	v_lshl_add_u64 v[248:249], s[72:73], 0, v[138:139]
	s_mov_b32 m0, s53
	s_nop 0
	global_load_lds_dwordx4 v[248:249], off
	s_waitcnt vmcnt(4)
	s_waitcnt lgkmcnt(0)
	s_barrier
	s_setprio 1
	s_waitcnt lgkmcnt(0)
	v_mfma_f32_16x16x32_bf16 v[60:63], v[180:183], v[212:215], v[60:63]
	v_mfma_f32_16x16x32_bf16 v[56:59], v[188:191], v[212:215], v[56:59]
	v_mfma_f32_16x16x32_bf16 v[52:55], v[180:183], v[220:223], v[52:55]
	v_mfma_f32_16x16x32_bf16 v[44:47], v[188:191], v[220:223], v[44:47]
	v_mfma_f32_16x16x32_bf16 v[36:39], v[180:183], v[228:231], v[36:39]
	v_mfma_f32_16x16x32_bf16 v[28:31], v[188:191], v[228:231], v[28:31]
	v_mfma_f32_16x16x32_bf16 v[20:23], v[180:183], v[236:239], v[20:23]
	v_mfma_f32_16x16x32_bf16 v[12:15], v[188:191], v[236:239], v[12:15]
	v_mfma_f32_16x16x32_bf16 v[60:63], v[184:187], v[216:219], v[60:63]
	v_mfma_f32_16x16x32_bf16 v[56:59], v[192:195], v[216:219], v[56:59]
	v_mfma_f32_16x16x32_bf16 v[52:55], v[184:187], v[224:227], v[52:55]
	v_mfma_f32_16x16x32_bf16 v[44:47], v[192:195], v[224:227], v[44:47]
	v_mfma_f32_16x16x32_bf16 v[36:39], v[184:187], v[232:235], v[36:39]
	v_mfma_f32_16x16x32_bf16 v[28:31], v[192:195], v[232:235], v[28:31]
	v_mfma_f32_16x16x32_bf16 v[20:23], v[184:187], v[240:243], v[20:23]
	v_mfma_f32_16x16x32_bf16 v[12:15], v[192:195], v[240:243], v[12:15]
	s_setprio 0
	s_setprio 1
	v_mfma_f32_16x16x32_bf16 v[48:51], v[196:199], v[212:215], v[48:51]
	v_mfma_f32_16x16x32_bf16 v[40:43], v[204:207], v[212:215], v[40:43]
	v_mfma_f32_16x16x32_bf16 v[32:35], v[196:199], v[220:223], v[32:35]
	v_mfma_f32_16x16x32_bf16 v[24:27], v[204:207], v[220:223], v[24:27]
	v_mfma_f32_16x16x32_bf16 v[16:19], v[196:199], v[228:231], v[16:19]
	v_mfma_f32_16x16x32_bf16 v[8:11], v[204:207], v[228:231], v[8:11]
	v_mfma_f32_16x16x32_bf16 v[4:7], v[196:199], v[236:239], v[4:7]
	v_mfma_f32_16x16x32_bf16 v[0:3], v[204:207], v[236:239], v[0:3]
	v_mfma_f32_16x16x32_bf16 v[48:51], v[200:203], v[216:219], v[48:51]
	v_mfma_f32_16x16x32_bf16 v[40:43], v[208:211], v[216:219], v[40:43]
	v_mfma_f32_16x16x32_bf16 v[32:35], v[200:203], v[224:227], v[32:35]
	v_mfma_f32_16x16x32_bf16 v[24:27], v[208:211], v[224:227], v[24:27]
	v_mfma_f32_16x16x32_bf16 v[16:19], v[200:203], v[232:235], v[16:19]
	v_mfma_f32_16x16x32_bf16 v[8:11], v[208:211], v[232:235], v[8:11]
	v_mfma_f32_16x16x32_bf16 v[4:7], v[200:203], v[240:243], v[4:7]
	v_mfma_f32_16x16x32_bf16 v[0:3], v[208:211], v[240:243], v[0:3]
	s_setprio 0
	s_barrier
	ds_read_b128 v[180:183], v170
	ds_read_b128 v[184:187], v171
	ds_read_b128 v[188:191], v172
	ds_read_b128 v[192:195], v173
	ds_read_b128 v[196:199], v176
	ds_read_b128 v[200:203], v177
	ds_read_b128 v[204:207], v178
	ds_read_b128 v[208:211], v179
	s_mov_b32 m0, s49
	v_lshl_add_u64 v[248:249], s[44:45], 0, v[128:129]
	ds_read_b128 v[212:215], v160 offset:32768
	ds_read_b128 v[216:219], v160 offset:33792
	ds_read_b128 v[220:223], v160 offset:34816
	ds_read_b128 v[224:227], v160 offset:35840
	ds_read_b128 v[228:231], v160 offset:36864
	ds_read_b128 v[232:235], v160 offset:37888
	ds_read_b128 v[236:239], v160 offset:38912
	ds_read_b128 v[240:243], v160 offset:39936
	global_load_lds_dwordx4 v[248:249], off
	v_lshl_add_u64 v[248:249], s[44:45], 0, v[130:131]
	s_mov_b32 m0, s54
	s_nop 0
	global_load_lds_dwordx4 v[248:249], off
	v_lshl_add_u64 v[248:249], s[44:45], 0, v[132:133]
	s_mov_b32 m0, s55
	s_nop 0
	global_load_lds_dwordx4 v[248:249], off
	v_lshl_add_u64 v[248:249], s[44:45], 0, v[134:135]
	s_mov_b32 m0, s56
	s_nop 0
	global_load_lds_dwordx4 v[248:249], off
	s_waitcnt lgkmcnt(8)
	s_barrier
	s_waitcnt lgkmcnt(0)
	s_setprio 1
	s_waitcnt lgkmcnt(0)
	v_mfma_f32_16x16x32_bf16 v[124:127], v[180:183], v[212:215], v[124:127]
	v_mfma_f32_16x16x32_bf16 v[120:123], v[188:191], v[212:215], v[120:123]
	v_mfma_f32_16x16x32_bf16 v[116:119], v[180:183], v[220:223], v[116:119]
	v_mfma_f32_16x16x32_bf16 v[108:111], v[188:191], v[220:223], v[108:111]
	v_mfma_f32_16x16x32_bf16 v[100:103], v[180:183], v[228:231], v[100:103]
	v_mfma_f32_16x16x32_bf16 v[92:95], v[188:191], v[228:231], v[92:95]
	v_mfma_f32_16x16x32_bf16 v[84:87], v[180:183], v[236:239], v[84:87]
	v_mfma_f32_16x16x32_bf16 v[76:79], v[188:191], v[236:239], v[76:79]
	v_mfma_f32_16x16x32_bf16 v[124:127], v[184:187], v[216:219], v[124:127]
	v_mfma_f32_16x16x32_bf16 v[120:123], v[192:195], v[216:219], v[120:123]
	v_mfma_f32_16x16x32_bf16 v[116:119], v[184:187], v[224:227], v[116:119]
	v_mfma_f32_16x16x32_bf16 v[108:111], v[192:195], v[224:227], v[108:111]
	v_mfma_f32_16x16x32_bf16 v[100:103], v[184:187], v[232:235], v[100:103]
	v_mfma_f32_16x16x32_bf16 v[92:95], v[192:195], v[232:235], v[92:95]
	v_mfma_f32_16x16x32_bf16 v[84:87], v[184:187], v[240:243], v[84:87]
	v_mfma_f32_16x16x32_bf16 v[76:79], v[192:195], v[240:243], v[76:79]
	s_setprio 0
	s_setprio 1
	v_mfma_f32_16x16x32_bf16 v[112:115], v[196:199], v[212:215], v[112:115]
	v_mfma_f32_16x16x32_bf16 v[104:107], v[204:207], v[212:215], v[104:107]
	v_mfma_f32_16x16x32_bf16 v[96:99], v[196:199], v[220:223], v[96:99]
	v_mfma_f32_16x16x32_bf16 v[88:91], v[204:207], v[220:223], v[88:91]
	v_mfma_f32_16x16x32_bf16 v[80:83], v[196:199], v[228:231], v[80:83]
	v_mfma_f32_16x16x32_bf16 v[72:75], v[204:207], v[228:231], v[72:75]
	v_mfma_f32_16x16x32_bf16 v[68:71], v[196:199], v[236:239], v[68:71]
	v_mfma_f32_16x16x32_bf16 v[64:67], v[204:207], v[236:239], v[64:67]
	v_mfma_f32_16x16x32_bf16 v[112:115], v[200:203], v[216:219], v[112:115]
	v_mfma_f32_16x16x32_bf16 v[104:107], v[208:211], v[216:219], v[104:107]
	v_mfma_f32_16x16x32_bf16 v[96:99], v[200:203], v[224:227], v[96:99]
	v_mfma_f32_16x16x32_bf16 v[88:91], v[208:211], v[224:227], v[88:91]
	v_mfma_f32_16x16x32_bf16 v[80:83], v[200:203], v[232:235], v[80:83]
	v_mfma_f32_16x16x32_bf16 v[72:75], v[208:211], v[232:235], v[72:75]
	v_mfma_f32_16x16x32_bf16 v[68:71], v[200:203], v[240:243], v[68:71]
	v_mfma_f32_16x16x32_bf16 v[64:67], v[208:211], v[240:243], v[64:67]
	s_setprio 0
	s_barrier
	s_mov_b32 m0, s58
	v_lshl_add_u64 v[244:245], v[244:245], 0, s[14:15]
	s_add_u32 s42, s42, 0x100080
	ds_read_b128 v[212:215], v160 offset:49152
	ds_read_b128 v[216:219], v160 offset:50176
	ds_read_b128 v[220:223], v160 offset:51200
	ds_read_b128 v[224:227], v160 offset:52224
	ds_read_b128 v[228:231], v160 offset:53248
	ds_read_b128 v[232:235], v160 offset:54272
	ds_read_b128 v[236:239], v160 offset:55296
	ds_read_b128 v[240:243], v160 offset:56320
	global_load_lds_dwordx4 v[244:245], off
	v_lshl_add_u64 v[244:245], v[246:247], 0, s[14:15]
	s_mov_b32 m0, s59
	s_addc_u32 s43, s43, 0
	global_load_lds_dwordx4 v[244:245], off
	v_lshl_add_u64 v[244:245], s[42:43], 0, v[136:137]
	s_mov_b32 m0, s60
	s_nop 0
	global_load_lds_dwordx4 v[244:245], off
	v_lshl_add_u64 v[244:245], s[42:43], 0, v[138:139]
	s_mov_b32 m0, s61
	s_nop 0
	global_load_lds_dwordx4 v[244:245], off
	s_waitcnt vmcnt(4)
	s_waitcnt lgkmcnt(0)
	s_barrier
	s_setprio 1
	s_waitcnt lgkmcnt(0)
	v_mfma_f32_16x16x32_bf16 v[60:63], v[180:183], v[212:215], v[60:63]
	v_mfma_f32_16x16x32_bf16 v[56:59], v[188:191], v[212:215], v[56:59]
	v_mfma_f32_16x16x32_bf16 v[52:55], v[180:183], v[220:223], v[52:55]
	v_mfma_f32_16x16x32_bf16 v[44:47], v[188:191], v[220:223], v[44:47]
	v_mfma_f32_16x16x32_bf16 v[36:39], v[180:183], v[228:231], v[36:39]
	v_mfma_f32_16x16x32_bf16 v[28:31], v[188:191], v[228:231], v[28:31]
	v_mfma_f32_16x16x32_bf16 v[20:23], v[180:183], v[236:239], v[20:23]
	v_mfma_f32_16x16x32_bf16 v[12:15], v[188:191], v[236:239], v[12:15]
	v_mfma_f32_16x16x32_bf16 v[60:63], v[184:187], v[216:219], v[60:63]
	v_mfma_f32_16x16x32_bf16 v[56:59], v[192:195], v[216:219], v[56:59]
	v_mfma_f32_16x16x32_bf16 v[52:55], v[184:187], v[224:227], v[52:55]
	v_mfma_f32_16x16x32_bf16 v[44:47], v[192:195], v[224:227], v[44:47]
	v_mfma_f32_16x16x32_bf16 v[36:39], v[184:187], v[232:235], v[36:39]
	v_mfma_f32_16x16x32_bf16 v[28:31], v[192:195], v[232:235], v[28:31]
	v_mfma_f32_16x16x32_bf16 v[20:23], v[184:187], v[240:243], v[20:23]
	v_mfma_f32_16x16x32_bf16 v[12:15], v[192:195], v[240:243], v[12:15]
	s_setprio 0
	s_setprio 1
	v_mfma_f32_16x16x32_bf16 v[48:51], v[196:199], v[212:215], v[48:51]
	v_mfma_f32_16x16x32_bf16 v[40:43], v[204:207], v[212:215], v[40:43]
	v_mfma_f32_16x16x32_bf16 v[32:35], v[196:199], v[220:223], v[32:35]
	v_mfma_f32_16x16x32_bf16 v[24:27], v[204:207], v[220:223], v[24:27]
	v_mfma_f32_16x16x32_bf16 v[16:19], v[196:199], v[228:231], v[16:19]
	v_mfma_f32_16x16x32_bf16 v[8:11], v[204:207], v[228:231], v[8:11]
	v_mfma_f32_16x16x32_bf16 v[4:7], v[196:199], v[236:239], v[4:7]
	v_mfma_f32_16x16x32_bf16 v[0:3], v[204:207], v[236:239], v[0:3]
	v_mfma_f32_16x16x32_bf16 v[48:51], v[200:203], v[216:219], v[48:51]
	v_mfma_f32_16x16x32_bf16 v[40:43], v[208:211], v[216:219], v[40:43]
	v_mfma_f32_16x16x32_bf16 v[32:35], v[200:203], v[224:227], v[32:35]
	v_mfma_f32_16x16x32_bf16 v[24:27], v[208:211], v[224:227], v[24:27]
	v_mfma_f32_16x16x32_bf16 v[16:19], v[200:203], v[232:235], v[16:19]
	v_mfma_f32_16x16x32_bf16 v[8:11], v[208:211], v[232:235], v[8:11]
	v_mfma_f32_16x16x32_bf16 v[4:7], v[200:203], v[240:243], v[4:7]
	v_mfma_f32_16x16x32_bf16 v[0:3], v[208:211], v[240:243], v[0:3]
	s_setprio 0
	s_barrier
	s_add_i32 s71, s71, 2
	s_add_u32 s40, s40, 0x100
	s_addc_u32 s41, s41, 0
	s_cmp_gt_u32 s71, 61
	s_cbranch_scc0 .LBB0_1845
	s_getpc_b64 s[94:95]
	v_mbcnt_lo_u32_b32 v254, -1, 0
	v_mbcnt_hi_u32_b32 v254, -1, v254
	v_lshlrev_b32_e32 v254, 7, v254
	global_load_dword v255, v254, s[94:95]
	v_lshl_add_u32 v152, s20, 8, v159
	v_ashrrev_i32_e32 v153, 31, v152
	v_lshl_or_b32 v150, s6, 8, v161
	v_lshlrev_b64 v[154:155], 11, v[152:153]
	v_ashrrev_i32_e32 v151, 31, v150
	v_lshl_add_u64 v[154:155], s[12:13], 0, v[154:155]
	v_lshl_add_u64 v[154:155], v[150:151], 1, v[154:155]
	v_cmp_gt_i32_e32 vcc, s57, v150
	s_and_saveexec_b64 s[6:7], vcc
	s_cbranch_execz .LBB0_1848
	v_cvt_pk_bf16_f32 v124, v124, v125
	v_cvt_pk_bf16_f32 v125, v126, v127
	v_cvt_pk_bf16_f32 v126, v120, v121
	v_cvt_pk_bf16_f32 v127, v122, v123
	flat_store_dwordx4 v[154:155], v[124:127]

.LBB0_2116:
	s_getpc_b64 s[94:95]
	v_mbcnt_lo_u32_b32 v254, -1, 0
	v_mbcnt_hi_u32_b32 v254, -1, v254
	v_lshlrev_b32_e32 v254, 8, v254
	global_load_dword v255, v254, s[94:95]
	global_load_dword v255, v254, s[94:95] offset:128
	s_add_i32 s73, s73, 1
	s_mul_i32 s8, s73, s66
	s_mul_hi_u32 s9, s73, s3
	s_add_i32 s9, s9, s8
	s_mul_i32 s8, s73, s3
	s_add_u32 s30, s8, s2
	s_addc_u32 s31, s9, s67
	v_cmp_gt_i64_e64 s[8:9], s[30:31], v[108:109]
	v_cmp_lt_i64_e64 s[10:11], s[30:31], v[106:107]
	s_and_b64 vcc, exec, s[8:9]
	s_cbranch_vccnz .LBB0_2118
	s_ashr_i32 s15, s30, 31
	s_lshr_b32 s15, s15, 29
	s_add_i32 s15, s30, s15
	s_ashr_i32 s22, s15, 3
	s_and_b32 s15, s15, -8
	s_sub_i32 s15, s30, s15
	s_lshr_b32 s28, s15, 31
	s_or_b32 s28, s28, 0x60
	s_mul_i32 s15, s28, s15
	s_add_i32 s15, s15, s22
	s_mul_hi_i32 s22, s15, 0x2aaaaaab
	s_lshr_b32 s28, s22, 31
	s_ashr_i32 s22, s22, 4
	s_add_i32 s22, s22, s28
	s_lshl_b32 s29, s22, 3
	s_sub_i32 s28, 64, s29
	s_min_i32 s30, s28, 8
	s_abs_i32 s28, s30
	v_cvt_f32_u32_e32 v0, s28
	s_sub_i32 s34, 0, s28
	s_mulk_i32 s22, 0x60
	s_sub_i32 s15, s15, s22
	v_rcp_iflag_f32_e32 v0, v0
	s_abs_i32 s22, s15
	s_xor_b32 s31, s15, s30
	s_ashr_i32 s31, s31, 31
	v_mul_f32_e32 v0, 0x4f7ffffe, v0
	v_cvt_u32_f32_e32 v0, v0
	s_nop 0
	v_readfirstlane_b32 s35, v0
	s_mul_i32 s34, s34, s35
	s_mul_hi_u32 s34, s35, s34
	s_add_i32 s35, s35, s34
	s_mul_hi_u32 s34, s22, s35
	s_mul_i32 s35, s34, s28
	s_sub_i32 s22, s22, s35
	s_add_i32 s36, s34, 1
	s_sub_i32 s35, s22, s28
	s_cmp_ge_u32 s22, s28
	s_cselect_b32 s34, s36, s34
	s_cselect_b32 s22, s35, s22
	s_add_i32 s35, s34, 1
	s_cmp_ge_u32 s22, s28
	s_cselect_b32 s22, s35, s34
	s_xor_b32 s22, s22, s31
	s_sub_i32 s28, s22, s31
	s_mul_i32 s22, s28, s30
	s_sub_i32 s15, s15, s22
	s_add_i32 s74, s15, s29

.LBB0_2141:
	s_getpc_b64 s[94:95]
	v_mbcnt_lo_u32_b32 v254, -1, 0
	v_mbcnt_hi_u32_b32 v254, -1, v254
	v_lshlrev_b32_e32 v254, 7, v254
	global_load_dword v255, v254, s[94:95]
	s_mulk_i32 s54, 0xc0
	v_add_u32_e32 v136, s54, v117
	v_lshl_or_b32 v112, s14, 8, v119
	v_mov_b64_e32 v[114:115], s[18:19]
	v_ashrrev_i32_e32 v113, 31, v112
	v_mad_i64_i32 v[114:115], s[10:11], v136, s71, v[114:115]
	v_lshl_add_u64 v[114:115], v[112:113], 1, v[114:115]
	v_cmp_gt_i32_e32 vcc, s72, v112
	s_and_saveexec_b64 s[10:11], vcc
	s_cbranch_execz .LBB0_2143
	v_cvt_pk_bf16_f32 v92, v92, v93
	v_cvt_pk_bf16_f32 v93, v94, v95
	v_cvt_pk_bf16_f32 v94, v88, v89
	v_cvt_pk_bf16_f32 v95, v90, v91
	flat_store_dwordx4 v[114:115], v[92:95]

.LBB0_3212:
	s_getpc_b64 s[94:95]
	v_mbcnt_lo_u32_b32 v254, -1, 0
	v_mbcnt_hi_u32_b32 v254, -1, v254
	v_lshlrev_b32_e32 v254, 8, v254
	global_load_dword v255, v254, s[94:95]
	global_load_dword v255, v254, s[94:95] offset:128
	s_add_i32 s82, s82, 1
	s_mul_i32 s8, s82, s77
	s_mul_hi_u32 s9, s82, s3
	s_add_i32 s9, s9, s8
	s_mul_i32 s8, s82, s3
	s_add_u32 s44, s8, s2
	s_addc_u32 s45, s9, s78
	v_cmp_gt_i64_e64 s[8:9], s[44:45], v[108:109]
	v_cmp_lt_i64_e64 s[10:11], s[44:45], v[106:107]
	s_and_b64 vcc, exec, s[8:9]
	s_cbranch_vccnz .LBB0_3214
	s_ashr_i32 s15, s44, 31
	s_lshr_b32 s15, s15, 29
	s_add_i32 s15, s44, s15
	s_ashr_i32 s24, s15, 3
	s_and_b32 s15, s15, -8
	s_sub_i32 s15, s44, s15
	s_lshr_b32 s42, s15, 31
	s_or_b32 s42, s42, 32
	s_mul_i32 s15, s42, s15
	s_add_i32 s15, s15, s24
	s_ashr_i32 s24, s15, 31
	s_lshr_b32 s24, s24, 27
	s_add_i32 s24, s15, s24
	s_ashr_i32 s42, s24, 5
	s_lshl_b32 s43, s42, 3
	s_sub_i32 s42, 64, s43
	s_min_i32 s44, s42, 8
	s_abs_i32 s42, s44
	v_cvt_f32_u32_e32 v0, s42
	s_sub_i32 s46, 0, s42
	s_andn2_b32 s24, s24, 31
	s_sub_i32 s15, s15, s24
	v_rcp_iflag_f32_e32 v0, v0
	s_abs_i32 s24, s15
	s_xor_b32 s45, s15, s44
	s_ashr_i32 s45, s45, 31
	v_mul_f32_e32 v0, 0x4f7ffffe, v0
	v_cvt_u32_f32_e32 v0, v0
	s_nop 0
	v_readfirstlane_b32 s47, v0
	s_mul_i32 s46, s46, s47
	s_mul_hi_u32 s46, s47, s46
	s_add_i32 s47, s47, s46
	s_mul_hi_u32 s46, s24, s47
	s_mul_i32 s47, s46, s42
	s_sub_i32 s24, s24, s47
	s_add_i32 s48, s46, 1
	s_sub_i32 s47, s24, s42
	s_cmp_ge_u32 s24, s42
	s_cselect_b32 s46, s48, s46
	s_cselect_b32 s24, s47, s24
	s_add_i32 s47, s46, 1
	s_cmp_ge_u32 s24, s42
	s_cselect_b32 s24, s47, s46
	s_xor_b32 s24, s24, s45
	s_sub_i32 s42, s24, s45
	s_mul_i32 s24, s42, s44
	s_sub_i32 s15, s15, s24
	s_add_i32 s83, s15, s43

.LBB0_3237:
	s_getpc_b64 s[94:95]
	v_mbcnt_lo_u32_b32 v254, -1, 0
	v_mbcnt_hi_u32_b32 v254, -1, v254
	v_lshlrev_b32_e32 v254, 7, v254
	global_load_dword v255, v254, s[94:95]
	s_mulk_i32 s60, 0xc0
	v_add_u32_e32 v114, s60, v119
	v_ashrrev_i32_e32 v115, 31, v114
	v_lshl_or_b32 v112, s14, 8, v121
	v_lshlrev_b64 v[116:117], 11, v[114:115]
	v_ashrrev_i32_e32 v113, 31, v112
	v_lshl_add_u64 v[116:117], s[18:19], 0, v[116:117]
	v_lshl_add_u64 v[116:117], v[112:113], 1, v[116:117]
	v_cmp_gt_i32_e32 vcc, s72, v112
	s_and_saveexec_b64 s[10:11], vcc
	s_cbranch_execz .LBB0_3239
	v_cvt_pk_bf16_f32 v92, v92, v93
	v_cvt_pk_bf16_f32 v93, v94, v95
	v_cvt_pk_bf16_f32 v94, v88, v89
	v_cvt_pk_bf16_f32 v95, v90, v91
	flat_store_dwordx4 v[116:117], v[92:95]

.LBB0_3362:
	s_getpc_b64 s[94:95]
	v_mbcnt_lo_u32_b32 v254, -1, 0
	v_mbcnt_hi_u32_b32 v254, -1, v254
	v_lshlrev_b32_e32 v254, 8, v254
	global_load_dword v255, v254, s[94:95]
	global_load_dword v255, v254, s[94:95] offset:128
	s_add_i32 s82, s82, 1
	s_mul_i32 s8, s82, s75
	s_mul_hi_u32 s9, s82, s3
	s_add_i32 s9, s9, s8
	s_mul_i32 s8, s82, s3
	s_add_u32 s10, s8, s2
	s_addc_u32 s11, s9, s76
	v_cmp_gt_i64_e64 s[8:9], s[10:11], v[140:141]
	s_and_b64 vcc, exec, s[8:9]
	s_cbranch_vccnz .LBB0_3364
	s_ashr_i32 s11, s10, 31
	s_lshr_b32 s11, s11, 29
	s_add_i32 s11, s10, s11
	s_ashr_i32 s20, s11, 3
	s_and_b32 s11, s11, -8
	s_sub_i32 s10, s10, s11
	s_lshr_b32 s11, s10, 31
	s_or_b32 s11, s11, 0x60
	s_mul_i32 s10, s11, s10
	s_add_i32 s10, s10, s20
	s_ashr_i32 s11, s10, 31
	s_lshr_b32 s11, s11, 25
	s_add_i32 s11, s10, s11
	s_ashr_i32 s20, s11, 7
	s_lshl_b32 s20, s20, 3
	s_sub_i32 s30, 48, s20
	s_min_i32 s31, s30, 8
	s_abs_i32 s30, s31
	v_cvt_f32_u32_e32 v0, s30
	s_sub_i32 s35, 0, s30
	s_and_b32 s11, s11, 0xffffff80
	s_sub_i32 s10, s10, s11
	v_rcp_iflag_f32_e32 v0, v0
	s_abs_i32 s11, s10
	s_xor_b32 s34, s10, s31
	s_ashr_i32 s34, s34, 31
	v_mul_f32_e32 v0, 0x4f7ffffe, v0
	v_cvt_u32_f32_e32 v0, v0
	s_nop 0
	v_readfirstlane_b32 s36, v0
	s_mul_i32 s35, s35, s36
	s_mul_hi_u32 s35, s36, s35
	s_add_i32 s36, s36, s35
	s_mul_hi_u32 s35, s11, s36
	s_mul_i32 s36, s35, s30
	s_sub_i32 s11, s11, s36
	s_add_i32 s37, s35, 1
	s_sub_i32 s36, s11, s30
	s_cmp_ge_u32 s11, s30
	s_cselect_b32 s35, s37, s35
	s_cselect_b32 s11, s36, s11
	s_add_i32 s36, s35, 1
	s_cmp_ge_u32 s11, s30
	s_cselect_b32 s11, s36, s35
	s_xor_b32 s11, s11, s34
	s_sub_i32 s30, s11, s34
	s_mul_i32 s11, s30, s31
	s_sub_i32 s10, s10, s11
	s_add_i32 s34, s10, s20

.LBB0_3483:
	ds_read_b128 v[142:145], v125
	ds_read_b128 v[146:149], v126
	ds_read_b128 v[150:153], v127
	ds_read_b128 v[154:157], v128
	ds_read_b128 v[158:161], v129
	ds_read_b128 v[162:165], v130
	ds_read_b128 v[166:169], v131
	ds_read_b128 v[170:173], v132
	s_add_u32 s34, s26, s6
	s_addc_u32 s35, s27, s7
	s_add_u32 s34, s34, 0x100
	s_addc_u32 s35, s35, 0
	s_add_u32 s65, s62, s6
	s_addc_u32 s66, s63, s7
	s_cmpk_eq_i32 s6, 0x1f00
	s_cselect_b32 s37, s29, s35
	s_cselect_b32 s36, s28, s34
	s_cselect_b32 s35, s13, s66
	s_cselect_b32 s34, s25, s65
	s_mov_b32 m0, s58
	v_lshl_add_u64 v[200:201], v[120:121], 0, s[6:7]
	ds_read_b128 v[176:179], v123
	ds_read_b128 v[180:183], v123 offset:1024
	ds_read_b128 v[184:187], v123 offset:2048
	ds_read_b128 v[188:191], v123 offset:3072
	ds_read_b128 v[192:195], v123 offset:4096
	ds_read_b128 v[196:199], v123 offset:5120
	global_load_lds_dwordx4 v[200:201], off
	v_lshl_add_u64 v[200:201], v[118:119], 0, s[6:7]
	s_mov_b32 m0, s59
	s_nop 0
	global_load_lds_dwordx4 v[200:201], off
	v_lshl_add_u64 v[200:201], v[116:117], 0, s[6:7]
	s_mov_b32 m0, s60
	s_nop 0
	global_load_lds_dwordx4 v[200:201], off
	s_waitcnt lgkmcnt(6)
	s_barrier
	s_waitcnt lgkmcnt(0)
	s_setprio 1
	s_waitcnt lgkmcnt(0)
	v_mfma_f32_16x16x32_bf16 v[92:95], v[142:145], v[176:179], v[92:95]
	v_mfma_f32_16x16x32_bf16 v[88:91], v[150:153], v[176:179], v[88:91]
	v_mfma_f32_16x16x32_bf16 v[76:79], v[142:145], v[184:187], v[76:79]
	v_mfma_f32_16x16x32_bf16 v[72:75], v[150:153], v[184:187], v[72:75]
	v_mfma_f32_16x16x32_bf16 v[60:63], v[142:145], v[192:195], v[60:63]
	v_mfma_f32_16x16x32_bf16 v[56:59], v[150:153], v[192:195], v[56:59]
	v_mfma_f32_16x16x32_bf16 v[92:95], v[146:149], v[180:183], v[92:95]
	v_mfma_f32_16x16x32_bf16 v[88:91], v[154:157], v[180:183], v[88:91]
	v_mfma_f32_16x16x32_bf16 v[76:79], v[146:149], v[188:191], v[76:79]
	v_mfma_f32_16x16x32_bf16 v[72:75], v[154:157], v[188:191], v[72:75]
	v_mfma_f32_16x16x32_bf16 v[60:63], v[146:149], v[196:199], v[60:63]
	v_mfma_f32_16x16x32_bf16 v[56:59], v[154:157], v[196:199], v[56:59]
	s_setprio 0
	s_setprio 1
	v_mfma_f32_16x16x32_bf16 v[84:87], v[158:161], v[176:179], v[84:87]
	v_mfma_f32_16x16x32_bf16 v[80:83], v[166:169], v[176:179], v[80:83]
	v_mfma_f32_16x16x32_bf16 v[68:71], v[158:161], v[184:187], v[68:71]
	v_mfma_f32_16x16x32_bf16 v[64:67], v[166:169], v[184:187], v[64:67]
	v_mfma_f32_16x16x32_bf16 v[52:55], v[158:161], v[192:195], v[52:55]
	v_mfma_f32_16x16x32_bf16 v[48:51], v[166:169], v[192:195], v[48:51]
	v_mfma_f32_16x16x32_bf16 v[84:87], v[162:165], v[180:183], v[84:87]
	v_mfma_f32_16x16x32_bf16 v[80:83], v[170:173], v[180:183], v[80:83]
	v_mfma_f32_16x16x32_bf16 v[68:71], v[162:165], v[188:191], v[68:71]
	v_mfma_f32_16x16x32_bf16 v[64:67], v[170:173], v[188:191], v[64:67]
	v_mfma_f32_16x16x32_bf16 v[52:55], v[162:165], v[196:199], v[52:55]
	v_mfma_f32_16x16x32_bf16 v[48:51], v[170:173], v[196:199], v[48:51]
	s_setprio 0
	s_barrier
	s_mov_b32 m0, s43
	v_lshl_add_u64 v[200:201], s[34:35], 0, v[102:103]
	s_add_u32 s66, s34, 0x100000
	ds_read_b128 v[176:179], v123 offset:12288
	ds_read_b128 v[180:183], v123 offset:13312
	ds_read_b128 v[184:187], v123 offset:14336
	ds_read_b128 v[188:191], v123 offset:15360
	ds_read_b128 v[192:195], v123 offset:16384
	ds_read_b128 v[196:199], v123 offset:17408
	global_load_lds_dwordx4 v[200:201], off
	v_lshl_add_u64 v[202:203], s[34:35], 0, v[104:105]
	s_mov_b32 m0, s44
	s_addc_u32 s67, s35, 0
	global_load_lds_dwordx4 v[202:203], off
	v_lshl_add_u64 v[204:205], s[66:67], 0, v[102:103]
	s_mov_b32 m0, s45
	s_nop 0
	global_load_lds_dwordx4 v[204:205], off
	v_lshl_add_u64 v[204:205], s[66:67], 0, v[104:105]
	s_mov_b32 m0, s46
	s_nop 0
	global_load_lds_dwordx4 v[204:205], off
	s_waitcnt vmcnt(4)
	s_waitcnt lgkmcnt(0)
	s_barrier
	s_setprio 1
	s_waitcnt lgkmcnt(0)
	v_mfma_f32_16x16x32_bf16 v[44:47], v[142:145], v[176:179], v[44:47]
	v_mfma_f32_16x16x32_bf16 v[40:43], v[150:153], v[176:179], v[40:43]
	v_mfma_f32_16x16x32_bf16 v[28:31], v[142:145], v[184:187], v[28:31]
	v_mfma_f32_16x16x32_bf16 v[24:27], v[150:153], v[184:187], v[24:27]
	v_mfma_f32_16x16x32_bf16 v[12:15], v[142:145], v[192:195], v[12:15]
	v_mfma_f32_16x16x32_bf16 v[8:11], v[150:153], v[192:195], v[8:11]
	v_mfma_f32_16x16x32_bf16 v[44:47], v[146:149], v[180:183], v[44:47]
	v_mfma_f32_16x16x32_bf16 v[40:43], v[154:157], v[180:183], v[40:43]
	v_mfma_f32_16x16x32_bf16 v[28:31], v[146:149], v[188:191], v[28:31]
	v_mfma_f32_16x16x32_bf16 v[24:27], v[154:157], v[188:191], v[24:27]
	v_mfma_f32_16x16x32_bf16 v[12:15], v[146:149], v[196:199], v[12:15]
	v_mfma_f32_16x16x32_bf16 v[8:11], v[154:157], v[196:199], v[8:11]
	s_setprio 0
	s_setprio 1
	v_mfma_f32_16x16x32_bf16 v[36:39], v[158:161], v[176:179], v[36:39]
	v_mfma_f32_16x16x32_bf16 v[32:35], v[166:169], v[176:179], v[32:35]
	v_mfma_f32_16x16x32_bf16 v[20:23], v[158:161], v[184:187], v[20:23]
	v_mfma_f32_16x16x32_bf16 v[16:19], v[166:169], v[184:187], v[16:19]
	v_mfma_f32_16x16x32_bf16 v[4:7], v[158:161], v[192:195], v[4:7]
	v_mfma_f32_16x16x32_bf16 v[0:3], v[166:169], v[192:195], v[0:3]
	v_mfma_f32_16x16x32_bf16 v[36:39], v[162:165], v[180:183], v[36:39]
	v_mfma_f32_16x16x32_bf16 v[32:35], v[170:173], v[180:183], v[32:35]
	v_mfma_f32_16x16x32_bf16 v[20:23], v[162:165], v[188:191], v[20:23]
	v_mfma_f32_16x16x32_bf16 v[16:19], v[170:173], v[188:191], v[16:19]
	v_mfma_f32_16x16x32_bf16 v[4:7], v[162:165], v[196:199], v[4:7]
	v_mfma_f32_16x16x32_bf16 v[0:3], v[170:173], v[196:199], v[0:3]
	s_setprio 0
	s_barrier
	ds_read_b128 v[142:145], v133
	ds_read_b128 v[146:149], v134
	ds_read_b128 v[150:153], v135
	ds_read_b128 v[154:157], v136
	ds_read_b128 v[158:161], v137
	ds_read_b128 v[162:165], v138
	ds_read_b128 v[166:169], v139
	ds_read_b128 v[170:173], v140
	s_mov_b32 m0, s42
	v_lshl_add_u64 v[204:205], s[36:37], 0, v[96:97]
	ds_read_b128 v[176:179], v123 offset:32768
	ds_read_b128 v[180:183], v123 offset:33792
	ds_read_b128 v[184:187], v123 offset:34816
	ds_read_b128 v[188:191], v123 offset:35840
	ds_read_b128 v[192:195], v123 offset:36864
	ds_read_b128 v[196:199], v123 offset:37888
	global_load_lds_dwordx4 v[204:205], off
	v_lshl_add_u64 v[204:205], s[36:37], 0, v[98:99]
	s_mov_b32 m0, s47
	s_nop 0
	global_load_lds_dwordx4 v[204:205], off
	v_lshl_add_u64 v[204:205], s[36:37], 0, v[100:101]
	s_mov_b32 m0, s48
	s_nop 0
	global_load_lds_dwordx4 v[204:205], off
	s_waitcnt lgkmcnt(6)
	s_barrier
	s_waitcnt lgkmcnt(0)
	s_setprio 1
	s_waitcnt lgkmcnt(0)
	v_mfma_f32_16x16x32_bf16 v[92:95], v[142:145], v[176:179], v[92:95]
	v_mfma_f32_16x16x32_bf16 v[88:91], v[150:153], v[176:179], v[88:91]
	v_mfma_f32_16x16x32_bf16 v[76:79], v[142:145], v[184:187], v[76:79]
	v_mfma_f32_16x16x32_bf16 v[72:75], v[150:153], v[184:187], v[72:75]
	v_mfma_f32_16x16x32_bf16 v[60:63], v[142:145], v[192:195], v[60:63]
	v_mfma_f32_16x16x32_bf16 v[56:59], v[150:153], v[192:195], v[56:59]
	v_mfma_f32_16x16x32_bf16 v[92:95], v[146:149], v[180:183], v[92:95]
	v_mfma_f32_16x16x32_bf16 v[88:91], v[154:157], v[180:183], v[88:91]
	v_mfma_f32_16x16x32_bf16 v[76:79], v[146:149], v[188:191], v[76:79]
	v_mfma_f32_16x16x32_bf16 v[72:75], v[154:157], v[188:191], v[72:75]
	v_mfma_f32_16x16x32_bf16 v[60:63], v[146:149], v[196:199], v[60:63]
	v_mfma_f32_16x16x32_bf16 v[56:59], v[154:157], v[196:199], v[56:59]
	s_setprio 0
	s_setprio 1
	v_mfma_f32_16x16x32_bf16 v[84:87], v[158:161], v[176:179], v[84:87]
	v_mfma_f32_16x16x32_bf16 v[80:83], v[166:169], v[176:179], v[80:83]
	v_mfma_f32_16x16x32_bf16 v[68:71], v[158:161], v[184:187], v[68:71]
	v_mfma_f32_16x16x32_bf16 v[64:67], v[166:169], v[184:187], v[64:67]
	v_mfma_f32_16x16x32_bf16 v[52:55], v[158:161], v[192:195], v[52:55]
	v_mfma_f32_16x16x32_bf16 v[48:51], v[166:169], v[192:195], v[48:51]
	v_mfma_f32_16x16x32_bf16 v[84:87], v[162:165], v[180:183], v[84:87]
	v_mfma_f32_16x16x32_bf16 v[80:83], v[170:173], v[180:183], v[80:83]
	v_mfma_f32_16x16x32_bf16 v[68:71], v[162:165], v[188:191], v[68:71]
	v_mfma_f32_16x16x32_bf16 v[64:67], v[170:173], v[188:191], v[64:67]
	v_mfma_f32_16x16x32_bf16 v[52:55], v[162:165], v[196:199], v[52:55]
	v_mfma_f32_16x16x32_bf16 v[48:51], v[170:173], v[196:199], v[48:51]
	s_setprio 0
	s_barrier
	s_mov_b32 m0, s50
	v_lshl_add_u64 v[200:201], v[200:201], 0, s[10:11]
	s_add_u32 s34, s34, 0x100080
	ds_read_b128 v[176:179], v123 offset:45056
	ds_read_b128 v[180:183], v123 offset:46080
	ds_read_b128 v[184:187], v123 offset:47104
	ds_read_b128 v[188:191], v123 offset:48128
	ds_read_b128 v[192:195], v123 offset:49152
	ds_read_b128 v[196:199], v123 offset:50176
	global_load_lds_dwordx4 v[200:201], off
	v_lshl_add_u64 v[200:201], v[202:203], 0, s[10:11]
	s_mov_b32 m0, s51
	s_addc_u32 s35, s35, 0
	global_load_lds_dwordx4 v[200:201], off
	v_lshl_add_u64 v[200:201], s[34:35], 0, v[102:103]
	s_mov_b32 m0, s52
	s_nop 0
	global_load_lds_dwordx4 v[200:201], off
	v_lshl_add_u64 v[200:201], s[34:35], 0, v[104:105]
	s_mov_b32 m0, s53
	s_nop 0
	global_load_lds_dwordx4 v[200:201], off
	s_waitcnt vmcnt(4)
	s_waitcnt lgkmcnt(0)
	s_barrier
	s_setprio 1
	s_waitcnt lgkmcnt(0)
	v_mfma_f32_16x16x32_bf16 v[44:47], v[142:145], v[176:179], v[44:47]
	v_mfma_f32_16x16x32_bf16 v[40:43], v[150:153], v[176:179], v[40:43]
	v_mfma_f32_16x16x32_bf16 v[28:31], v[142:145], v[184:187], v[28:31]
	v_mfma_f32_16x16x32_bf16 v[24:27], v[150:153], v[184:187], v[24:27]
	v_mfma_f32_16x16x32_bf16 v[12:15], v[142:145], v[192:195], v[12:15]
	v_mfma_f32_16x16x32_bf16 v[8:11], v[150:153], v[192:195], v[8:11]
	v_mfma_f32_16x16x32_bf16 v[44:47], v[146:149], v[180:183], v[44:47]
	v_mfma_f32_16x16x32_bf16 v[40:43], v[154:157], v[180:183], v[40:43]
	v_mfma_f32_16x16x32_bf16 v[28:31], v[146:149], v[188:191], v[28:31]
	v_mfma_f32_16x16x32_bf16 v[24:27], v[154:157], v[188:191], v[24:27]
	v_mfma_f32_16x16x32_bf16 v[12:15], v[146:149], v[196:199], v[12:15]
	v_mfma_f32_16x16x32_bf16 v[8:11], v[154:157], v[196:199], v[8:11]
	s_setprio 0
	s_setprio 1
	v_mfma_f32_16x16x32_bf16 v[36:39], v[158:161], v[176:179], v[36:39]
	v_mfma_f32_16x16x32_bf16 v[32:35], v[166:169], v[176:179], v[32:35]
	v_mfma_f32_16x16x32_bf16 v[20:23], v[158:161], v[184:187], v[20:23]
	v_mfma_f32_16x16x32_bf16 v[16:19], v[166:169], v[184:187], v[16:19]
	v_mfma_f32_16x16x32_bf16 v[4:7], v[158:161], v[192:195], v[4:7]
	v_mfma_f32_16x16x32_bf16 v[0:3], v[166:169], v[192:195], v[0:3]
	v_mfma_f32_16x16x32_bf16 v[36:39], v[162:165], v[180:183], v[36:39]
	v_mfma_f32_16x16x32_bf16 v[32:35], v[170:173], v[180:183], v[32:35]
	v_mfma_f32_16x16x32_bf16 v[20:23], v[162:165], v[188:191], v[20:23]
	v_mfma_f32_16x16x32_bf16 v[16:19], v[170:173], v[188:191], v[16:19]
	v_mfma_f32_16x16x32_bf16 v[4:7], v[162:165], v[196:199], v[4:7]
	v_mfma_f32_16x16x32_bf16 v[0:3], v[170:173], v[196:199], v[0:3]
	s_setprio 0
	s_barrier
	s_add_i32 s64, s64, 2
	s_add_u32 s6, s6, 0x100
	s_addc_u32 s7, s7, 0
	s_cmp_gt_u32 s64, 61
	s_cbranch_scc0 .LBB0_3483
	s_getpc_b64 s[94:95]
	v_mbcnt_lo_u32_b32 v254, -1, 0
	v_mbcnt_hi_u32_b32 v254, -1, v254
	v_lshlrev_b32_e32 v254, 7, v254
	global_load_dword v255, v254, s[94:95]
	s_mul_i32 s6, s56, 0xc0
	v_add_u32_e32 v118, s6, v122
	v_ashrrev_i32_e32 v119, 31, v118
	v_lshl_or_b32 v116, s12, 8, v124
	v_lshlrev_b64 v[120:121], 11, v[118:119]
	v_ashrrev_i32_e32 v117, 31, v116
	v_lshl_add_u64 v[120:121], s[8:9], 0, v[120:121]
	v_lshl_add_u64 v[120:121], v[116:117], 1, v[120:121]
	v_cmp_gt_i32_e32 vcc, s49, v116
	s_and_saveexec_b64 s[6:7], vcc
	s_cbranch_execz .LBB0_3486
	v_cvt_pk_bf16_f32 v92, v92, v93
	v_cvt_pk_bf16_f32 v93, v94, v95
	v_cvt_pk_bf16_f32 v94, v88, v89
	v_cvt_pk_bf16_f32 v95, v90, v91
	flat_store_dwordx4 v[120:121], v[92:95]
